# strategy 2 (de-serialisation): prep0 adaLN GEMV issues the 16 weight-row loads of each loop trip together (was one load + full wait at a time); FMA order unchanged
# speedup vs baseline: 1.0065x; 1.0065x over previous
.LBB0_462:
	v_lshl_add_u64 v[32:33], v[30:31], 0, s[40:41]
	ds_read_b128 v[14:17], v37
	ds_read_b128 v[18:21], v37 offset:16
	ds_read_b128 v[38:41], v37 offset:4096
	ds_read_b128 v[42:45], v37 offset:4112
	ds_read_b128 v[46:49], v37 offset:8192
	ds_read_b128 v[50:53], v37 offset:8208
	global_load_dwordx4 v[76:79], v[32:33], off
	s_mov_b32 s12, 0x6000
	v_add_co_u32_e64 v204, s[0:1], s12, v32
	s_nop 1
	v_addc_co_u32_e64 v205, s[0:1], 0, v33, s[0:1]
	global_load_dwordx4 v[80:83], v[204:205], off
	s_mov_b32 s12, 0xc000
	v_add_co_u32_e64 v206, s[0:1], s12, v32
	s_nop 1
	v_addc_co_u32_e64 v207, s[0:1], 0, v33, s[0:1]
	global_load_dwordx4 v[84:87], v[206:207], off
	s_mov_b32 s12, 0x12000
	v_add_co_u32_e64 v208, s[0:1], s12, v32
	s_nop 1
	v_addc_co_u32_e64 v209, s[0:1], 0, v33, s[0:1]
	global_load_dwordx4 v[88:91], v[208:209], off
	s_mov_b32 s12, 0x18000
	v_add_co_u32_e64 v210, s[0:1], s12, v32
	s_nop 1
	v_addc_co_u32_e64 v211, s[0:1], 0, v33, s[0:1]
	global_load_dwordx4 v[92:95], v[210:211], off
	s_mov_b32 s12, 0x1e000
	v_add_co_u32_e64 v212, s[0:1], s12, v32
	s_nop 1
	v_addc_co_u32_e64 v213, s[0:1], 0, v33, s[0:1]
	global_load_dwordx4 v[96:99], v[212:213], off
	s_mov_b32 s12, 0x24000
	v_add_co_u32_e64 v214, s[0:1], s12, v32
	s_nop 1
	v_addc_co_u32_e64 v215, s[0:1], 0, v33, s[0:1]
	global_load_dwordx4 v[100:103], v[214:215], off
	s_mov_b32 s12, 0x2a000
	v_add_co_u32_e64 v216, s[0:1], s12, v32
	s_nop 1
	v_addc_co_u32_e64 v217, s[0:1], 0, v33, s[0:1]
	global_load_dwordx4 v[104:107], v[216:217], off
	s_mov_b32 s12, 0x30000
	v_add_co_u32_e64 v218, s[0:1], s12, v32
	s_nop 1
	v_addc_co_u32_e64 v219, s[0:1], 0, v33, s[0:1]
	global_load_dwordx4 v[108:111], v[218:219], off
	s_mov_b32 s12, 0x36000
	v_add_co_u32_e64 v220, s[0:1], s12, v32
	s_nop 1
	v_addc_co_u32_e64 v221, s[0:1], 0, v33, s[0:1]
	global_load_dwordx4 v[112:115], v[220:221], off
	s_mov_b32 s12, 0x3c000
	v_add_co_u32_e64 v222, s[0:1], s12, v32
	s_nop 1
	v_addc_co_u32_e64 v223, s[0:1], 0, v33, s[0:1]
	global_load_dwordx4 v[116:119], v[222:223], off
	s_mov_b32 s12, 0x42000
	v_add_co_u32_e64 v224, s[0:1], s12, v32
	s_nop 1
	v_addc_co_u32_e64 v225, s[0:1], 0, v33, s[0:1]
	global_load_dwordx4 v[120:123], v[224:225], off
	s_mov_b32 s12, 0x48000
	v_add_co_u32_e64 v226, s[0:1], s12, v32
	s_nop 1
	v_addc_co_u32_e64 v227, s[0:1], 0, v33, s[0:1]
	global_load_dwordx4 v[124:127], v[226:227], off
	s_mov_b32 s12, 0x4e000
	v_add_co_u32_e64 v228, s[0:1], s12, v32
	s_nop 1
	v_addc_co_u32_e64 v229, s[0:1], 0, v33, s[0:1]
	global_load_dwordx4 v[128:131], v[228:229], off
	s_mov_b32 s12, 0x54000
	v_add_co_u32_e64 v230, s[0:1], s12, v32
	s_nop 1
	v_addc_co_u32_e64 v231, s[0:1], 0, v33, s[0:1]
	global_load_dwordx4 v[132:135], v[230:231], off
	s_mov_b32 s12, 0x5a000
	v_add_co_u32_e64 v232, s[0:1], s12, v32
	s_nop 1
	v_addc_co_u32_e64 v233, s[0:1], 0, v33, s[0:1]
	global_load_dwordx4 v[54:57], v[232:233], off
	s_waitcnt vmcnt(8) lgkmcnt(0)
	v_pk_fma_f32 v[2:3], v[76:77], v[14:15], v[2:3] op_sel_hi:[1,0,1]
	v_pk_fma_f32 v[4:5], v[78:79], v[14:15], v[4:5] op_sel_hi:[1,0,1]
	v_pk_fma_f32 v[10:11], v[76:77], v[38:39], v[10:11] op_sel_hi:[1,0,1]
	v_pk_fma_f32 v[12:13], v[78:79], v[38:39], v[12:13] op_sel_hi:[1,0,1]
	v_pk_fma_f32 v[6:7], v[76:77], v[46:47], v[6:7] op_sel_hi:[1,0,1]
	v_pk_fma_f32 v[8:9], v[78:79], v[46:47], v[8:9] op_sel_hi:[1,0,1]
	v_pk_fma_f32 v[2:3], v[80:81], v[14:15], v[2:3] op_sel:[0,1,0]
	v_pk_fma_f32 v[4:5], v[82:83], v[14:15], v[4:5] op_sel:[0,1,0]
	v_pk_fma_f32 v[10:11], v[80:81], v[38:39], v[10:11] op_sel:[0,1,0]
	v_pk_fma_f32 v[12:13], v[82:83], v[38:39], v[12:13] op_sel:[0,1,0]
	v_pk_fma_f32 v[6:7], v[80:81], v[46:47], v[6:7] op_sel:[0,1,0]
	v_pk_fma_f32 v[8:9], v[82:83], v[46:47], v[8:9] op_sel:[0,1,0]
	v_pk_fma_f32 v[2:3], v[84:85], v[16:17], v[2:3] op_sel_hi:[1,0,1]
	v_pk_fma_f32 v[4:5], v[86:87], v[16:17], v[4:5] op_sel_hi:[1,0,1]
	v_pk_fma_f32 v[10:11], v[84:85], v[40:41], v[10:11] op_sel_hi:[1,0,1]
	v_pk_fma_f32 v[12:13], v[86:87], v[40:41], v[12:13] op_sel_hi:[1,0,1]
	v_pk_fma_f32 v[6:7], v[84:85], v[48:49], v[6:7] op_sel_hi:[1,0,1]
	v_pk_fma_f32 v[8:9], v[86:87], v[48:49], v[8:9] op_sel_hi:[1,0,1]
	v_pk_fma_f32 v[2:3], v[88:89], v[16:17], v[2:3] op_sel:[0,1,0]
	v_pk_fma_f32 v[4:5], v[90:91], v[16:17], v[4:5] op_sel:[0,1,0]
	v_pk_fma_f32 v[10:11], v[88:89], v[40:41], v[10:11] op_sel:[0,1,0]
	v_pk_fma_f32 v[12:13], v[90:91], v[40:41], v[12:13] op_sel:[0,1,0]
	v_pk_fma_f32 v[6:7], v[88:89], v[48:49], v[6:7] op_sel:[0,1,0]
	v_pk_fma_f32 v[8:9], v[90:91], v[48:49], v[8:9] op_sel:[0,1,0]
	v_pk_fma_f32 v[2:3], v[92:93], v[18:19], v[2:3] op_sel_hi:[1,0,1]
	v_pk_fma_f32 v[4:5], v[94:95], v[18:19], v[4:5] op_sel_hi:[1,0,1]
	v_pk_fma_f32 v[10:11], v[92:93], v[42:43], v[10:11] op_sel_hi:[1,0,1]
	v_pk_fma_f32 v[12:13], v[94:95], v[42:43], v[12:13] op_sel_hi:[1,0,1]
	v_pk_fma_f32 v[6:7], v[92:93], v[50:51], v[6:7] op_sel_hi:[1,0,1]
	v_pk_fma_f32 v[8:9], v[94:95], v[50:51], v[8:9] op_sel_hi:[1,0,1]
	v_pk_fma_f32 v[2:3], v[96:97], v[18:19], v[2:3] op_sel:[0,1,0]
	v_pk_fma_f32 v[4:5], v[98:99], v[18:19], v[4:5] op_sel:[0,1,0]
	v_pk_fma_f32 v[10:11], v[96:97], v[42:43], v[10:11] op_sel:[0,1,0]
	v_pk_fma_f32 v[12:13], v[98:99], v[42:43], v[12:13] op_sel:[0,1,0]
	v_pk_fma_f32 v[6:7], v[96:97], v[50:51], v[6:7] op_sel:[0,1,0]
	v_pk_fma_f32 v[8:9], v[98:99], v[50:51], v[8:9] op_sel:[0,1,0]
	v_pk_fma_f32 v[2:3], v[100:101], v[20:21], v[2:3] op_sel_hi:[1,0,1]
	v_pk_fma_f32 v[4:5], v[102:103], v[20:21], v[4:5] op_sel_hi:[1,0,1]
	v_pk_fma_f32 v[10:11], v[100:101], v[44:45], v[10:11] op_sel_hi:[1,0,1]
	v_pk_fma_f32 v[12:13], v[102:103], v[44:45], v[12:13] op_sel_hi:[1,0,1]
	v_pk_fma_f32 v[6:7], v[100:101], v[52:53], v[6:7] op_sel_hi:[1,0,1]
	v_pk_fma_f32 v[8:9], v[102:103], v[52:53], v[8:9] op_sel_hi:[1,0,1]
	v_pk_fma_f32 v[2:3], v[104:105], v[20:21], v[2:3] op_sel:[0,1,0]
	v_pk_fma_f32 v[4:5], v[106:107], v[20:21], v[4:5] op_sel:[0,1,0]
	v_pk_fma_f32 v[10:11], v[104:105], v[44:45], v[10:11] op_sel:[0,1,0]
	v_pk_fma_f32 v[12:13], v[106:107], v[44:45], v[12:13] op_sel:[0,1,0]
	v_pk_fma_f32 v[6:7], v[104:105], v[52:53], v[6:7] op_sel:[0,1,0]
	v_pk_fma_f32 v[8:9], v[106:107], v[52:53], v[8:9] op_sel:[0,1,0]
	ds_read_b128 v[14:17], v37 offset:32
	ds_read_b128 v[18:21], v37 offset:48
	ds_read_b128 v[38:41], v37 offset:4128
	ds_read_b128 v[42:45], v37 offset:4144
	ds_read_b128 v[46:49], v37 offset:8224
	ds_read_b128 v[50:53], v37 offset:8240
	s_waitcnt vmcnt(0) lgkmcnt(0)
	v_pk_fma_f32 v[2:3], v[108:109], v[14:15], v[2:3] op_sel_hi:[1,0,1]
	v_pk_fma_f32 v[4:5], v[110:111], v[14:15], v[4:5] op_sel_hi:[1,0,1]
	v_pk_fma_f32 v[10:11], v[108:109], v[38:39], v[10:11] op_sel_hi:[1,0,1]
	v_pk_fma_f32 v[12:13], v[110:111], v[38:39], v[12:13] op_sel_hi:[1,0,1]
	v_pk_fma_f32 v[6:7], v[108:109], v[46:47], v[6:7] op_sel_hi:[1,0,1]
	v_pk_fma_f32 v[8:9], v[110:111], v[46:47], v[8:9] op_sel_hi:[1,0,1]
	v_pk_fma_f32 v[2:3], v[112:113], v[14:15], v[2:3] op_sel:[0,1,0]
	v_pk_fma_f32 v[4:5], v[114:115], v[14:15], v[4:5] op_sel:[0,1,0]
	v_pk_fma_f32 v[10:11], v[112:113], v[38:39], v[10:11] op_sel:[0,1,0]
	v_pk_fma_f32 v[12:13], v[114:115], v[38:39], v[12:13] op_sel:[0,1,0]
	v_pk_fma_f32 v[6:7], v[112:113], v[46:47], v[6:7] op_sel:[0,1,0]
	v_pk_fma_f32 v[8:9], v[114:115], v[46:47], v[8:9] op_sel:[0,1,0]
	v_pk_fma_f32 v[2:3], v[116:117], v[16:17], v[2:3] op_sel_hi:[1,0,1]
	v_pk_fma_f32 v[4:5], v[118:119], v[16:17], v[4:5] op_sel_hi:[1,0,1]
	v_pk_fma_f32 v[10:11], v[116:117], v[40:41], v[10:11] op_sel_hi:[1,0,1]
	v_pk_fma_f32 v[12:13], v[118:119], v[40:41], v[12:13] op_sel_hi:[1,0,1]
	v_pk_fma_f32 v[6:7], v[116:117], v[48:49], v[6:7] op_sel_hi:[1,0,1]
	v_pk_fma_f32 v[8:9], v[118:119], v[48:49], v[8:9] op_sel_hi:[1,0,1]
	v_pk_fma_f32 v[2:3], v[120:121], v[16:17], v[2:3] op_sel:[0,1,0]
	v_pk_fma_f32 v[4:5], v[122:123], v[16:17], v[4:5] op_sel:[0,1,0]
	v_pk_fma_f32 v[10:11], v[120:121], v[40:41], v[10:11] op_sel:[0,1,0]
	v_pk_fma_f32 v[12:13], v[122:123], v[40:41], v[12:13] op_sel:[0,1,0]
	v_pk_fma_f32 v[6:7], v[120:121], v[48:49], v[6:7] op_sel:[0,1,0]
	v_pk_fma_f32 v[8:9], v[122:123], v[48:49], v[8:9] op_sel:[0,1,0]
	v_pk_fma_f32 v[2:3], v[124:125], v[18:19], v[2:3] op_sel_hi:[1,0,1]
	v_pk_fma_f32 v[4:5], v[126:127], v[18:19], v[4:5] op_sel_hi:[1,0,1]
	v_pk_fma_f32 v[10:11], v[124:125], v[42:43], v[10:11] op_sel_hi:[1,0,1]
	v_pk_fma_f32 v[12:13], v[126:127], v[42:43], v[12:13] op_sel_hi:[1,0,1]
	v_pk_fma_f32 v[6:7], v[124:125], v[50:51], v[6:7] op_sel_hi:[1,0,1]
	v_pk_fma_f32 v[8:9], v[126:127], v[50:51], v[8:9] op_sel_hi:[1,0,1]
	v_pk_fma_f32 v[2:3], v[128:129], v[18:19], v[2:3] op_sel:[0,1,0]
	v_pk_fma_f32 v[4:5], v[130:131], v[18:19], v[4:5] op_sel:[0,1,0]
	v_pk_fma_f32 v[10:11], v[128:129], v[42:43], v[10:11] op_sel:[0,1,0]
	v_pk_fma_f32 v[12:13], v[130:131], v[42:43], v[12:13] op_sel:[0,1,0]
	v_pk_fma_f32 v[6:7], v[128:129], v[50:51], v[6:7] op_sel:[0,1,0]
	v_pk_fma_f32 v[8:9], v[130:131], v[50:51], v[8:9] op_sel:[0,1,0]
	v_pk_fma_f32 v[2:3], v[132:133], v[20:21], v[2:3] op_sel_hi:[1,0,1]
	v_pk_fma_f32 v[4:5], v[134:135], v[20:21], v[4:5] op_sel_hi:[1,0,1]
	v_pk_fma_f32 v[10:11], v[132:133], v[44:45], v[10:11] op_sel_hi:[1,0,1]
	v_pk_fma_f32 v[12:13], v[134:135], v[44:45], v[12:13] op_sel_hi:[1,0,1]
	v_pk_fma_f32 v[6:7], v[132:133], v[52:53], v[6:7] op_sel_hi:[1,0,1]
	v_pk_fma_f32 v[8:9], v[134:135], v[52:53], v[8:9] op_sel_hi:[1,0,1]
	v_pk_fma_f32 v[2:3], v[54:55], v[20:21], v[2:3] op_sel:[0,1,0]
	v_pk_fma_f32 v[4:5], v[56:57], v[20:21], v[4:5] op_sel:[0,1,0]
	v_pk_fma_f32 v[10:11], v[54:55], v[44:45], v[10:11] op_sel:[0,1,0]
	v_pk_fma_f32 v[12:13], v[56:57], v[44:45], v[12:13] op_sel:[0,1,0]
	v_pk_fma_f32 v[6:7], v[54:55], v[52:53], v[6:7] op_sel:[0,1,0]
	v_pk_fma_f32 v[8:9], v[56:57], v[52:53], v[8:9] op_sel:[0,1,0]
	v_add_u32_e32 v37, 64, v37
	s_add_u32 s40, s40, 0x60000
	s_addc_u32 s41, s41, 0
	s_cmp_eq_u32 s40, 0x180000
	s_cbranch_scc0 .LBB0_462
	s_barrier
	ds_write_b128 v34, v[2:5] offset:12288
	ds_write_b128 v34, v[10:13] offset:12544
	ds_write_b128 v34, v[6:9] offset:12800
	s_waitcnt lgkmcnt(0)
	s_barrier
	s_and_saveexec_b64 s[0:1], vcc
	s_cbranch_execz .LBB0_460
	ds_read2st64_b32 v[2:3], v27 offset0:48 offset1:51
	s_mul_i32 s12, s11, 0x1800
	s_add_i32 s12, s12, s38
	v_readlane_b32 s48, v253, 3
	v_readlane_b32 s54, v253, 9
	s_waitcnt lgkmcnt(0)
	v_add_f32_e32 v2, 0, v2
	v_add_f32_e32 v4, v2, v3
	ds_read2st64_b32 v[2:3], v27 offset0:54 offset1:57
	v_readlane_b32 s55, v253, 10
	v_readlane_b32 s49, v253, 4
	v_readlane_b32 s50, v253, 5
	v_readlane_b32 s51, v253, 6
	s_waitcnt lgkmcnt(0)
	v_add_f32_e32 v2, v4, v2
	v_add_f32_e32 v4, v2, v3
	ds_read2st64_b32 v[2:3], v27 offset0:60 offset1:63
	v_readlane_b32 s52, v253, 7
	v_readlane_b32 s53, v253, 8
	v_readlane_b32 s56, v253, 11
	v_readlane_b32 s57, v253, 12
	s_waitcnt lgkmcnt(0)
	v_add_f32_e32 v2, v4, v2
	v_add_f32_e32 v4, v2, v3
	ds_read2st64_b32 v[2:3], v27 offset0:66 offset1:69
	v_readlane_b32 s58, v253, 13
	v_readlane_b32 s59, v253, 14
	v_readlane_b32 s60, v253, 15
	v_readlane_b32 s61, v253, 16
	s_waitcnt lgkmcnt(0)
	v_add_f32_e32 v2, v4, v2
	v_add_f32_e32 v4, v2, v3
	ds_read2st64_b32 v[2:3], v27 offset0:72 offset1:75
	v_readlane_b32 s62, v253, 17
	v_readlane_b32 s63, v253, 18
	s_waitcnt lgkmcnt(0)
	v_add_f32_e32 v2, v4, v2
	v_add_f32_e32 v4, v2, v3
	ds_read2st64_b32 v[2:3], v27 offset0:78 offset1:81
	s_waitcnt lgkmcnt(0)
	v_add_f32_e32 v2, v4, v2
	v_add_f32_e32 v4, v2, v3
	ds_read2st64_b32 v[2:3], v27 offset0:84 offset1:87
	s_waitcnt lgkmcnt(0)
	v_add_f32_e32 v2, v4, v2
	v_add_f32_e32 v4, v2, v3
	ds_read2st64_b32 v[2:3], v27 offset0:90 offset1:93
	s_waitcnt lgkmcnt(0)
	v_add_f32_e32 v2, v4, v2
	v_add_f32_e32 v4, v2, v3
	v_or_b32_e32 v2, s12, v35
	v_ashrrev_i32_e32 v3, 31, v2
	v_lshl_add_u64 v[2:3], v[2:3], 2, s[54:55]
	global_load_dword v2, v[2:3], off
	s_mov_b64 s[54:55], 0x7b50180
	s_waitcnt vmcnt(0)
	v_add_f32_e32 v4, v4, v2
	v_mad_u64_u32 v[2:3], s[12:13], s11, 3, v[0:1]
	s_movk_i32 s11, 0x1800
	v_mul_lo_u32 v2, v2, s11
	v_add_u32_e32 v2, s38, v2
	v_or_b32_e32 v2, v2, v35
	v_ashrrev_i32_e32 v3, 31, v2
	v_lshl_add_u64 v[2:3], v[2:3], 2, s[34:35]
	global_store_dword v[2:3], v4, off
	s_branch .LBB0_460
